# the seam counter wait moved inside the next GEMM's preamble, after its four weight-tile stage loads have issued (FFN-in, FFN-out, mixer-in): address set-up and weight loads overlap the wait
# speedup vs baseline: 1.0177x; 1.0068x over previous
.Lxb_noinv_1:
	v_cmp_eq_u32_e32 vcc, 0, v0
	s_and_saveexec_b64 s[0:1], vcc
	s_cbranch_execz .LBB0_332
	s_load_dwordx2 s[12:13], s[8:9], 0x98
	v_readlane_b32 s14, v255, 0
	v_readlane_b32 s15, v255, 48
	s_nop 0
	s_lshr_b32 s24, s14, 3
	s_and_b32 s24, s24, 7
	s_and_b32 s27, s14, 6
	s_lshl_b32 s27, s27, 2
	s_or_b32 s27, s27, s24
	s_and_b32 s30, s14, 3
	s_lshl_b32 s30, s30, 3
	s_or_b32 s30, s30, s24
	s_lshl_b32 s27, s27, 7
	s_add_u32 s27, s27, 0xc000
	v_readlane_b32 s35, v255, 45
	s_nop 0
	s_lshl_b32 s35, s35, 4
	s_add_u32 s15, s15, 8
	v_writelane_b32 v255, s15, 48
	v_mov_b32_e32 v0, s27
	s_waitcnt lgkmcnt(0)
	global_atomic_add v0, v189, s[12:13]
	v_writelane_b32 v255, s27, 50
	v_writelane_b32 v255, s15, 51
	s_mov_b32 s34, 0xd000
	v_writelane_b32 v255, s34, 52
	v_writelane_b32 v255, s35, 53
	v_writelane_b32 v255, s12, 54
	v_writelane_b32 v255, s13, 55

.LBB0_336:
	v_readlane_b32 s26, v255, 0
	s_waitcnt vmcnt(9)
	v_mov_b32_e32 v14, v147
	s_cmpk_lt_i32 s26, 0x2c0
	v_readfirstlane_b32 s7, v14
	s_cbranch_scc0 .LBB0_352
	v_lshlrev_b32_e32 v0, 4, v14
	v_add_u32_e32 v1, 0x2000, v0
	v_ashrrev_i32_e32 v2, 31, v1
	v_lshrrev_b32_e32 v2, 22, v2
	s_load_dwordx2 s[0:1], s[8:9], 0x98
	v_add_u32_e32 v2, v1, v2
	v_ashrrev_i32_e32 v8, 10, v2
	v_mul_i32_i24_e32 v2, 0x400, v8
	v_sub_u32_e32 v1, v1, v2
	s_mul_i32 s5, s70, 0x2800000
	v_lshrrev_b32_e32 v2, 4, v1
	s_waitcnt lgkmcnt(0)
	s_add_u32 s5, s0, s5
	v_bitop3_b32 v1, v2, v1, 32 bitop3:0x6c
	s_addc_u32 s6, s1, 0
	v_ashrrev_i32_e32 v2, 31, v1
	s_add_u32 s27, s0, 0x1000000
	v_lshrrev_b32_e32 v2, 26, v2
	s_mul_i32 s4, s2, 0xb00000
	s_addc_u32 s30, s1, 0
	v_add_u32_e32 v2, v1, v2
	v_lshlrev_b32_e32 v3, 3, v8
	s_add_u32 s4, s5, s4
	v_ashrrev_i32_e32 v9, 6, v2
	v_and_b32_e32 v3, -16, v3
	s_addc_u32 s5, s6, 0
	v_add_u32_e32 v3, v9, v3
	s_add_u32 s31, s4, 0xc800000
	v_and_b32_e32 v4, 3, v9
	s_mov_b32 s4, 0x1fffe0
	v_lshrrev_b32_e32 v5, 2, v3
	v_lshlrev_b32_e32 v6, 1, v3
	v_and_b32_e32 v2, 0xc0, v2
	v_and_or_b32 v4, v3, s4, v4
	v_and_b32_e32 v5, 4, v5
	v_and_b32_e32 v6, 24, v6
	v_sub_u32_e32 v1, v1, v2
	v_or3_b32 v4, v4, v5, v6
	v_lshlrev_b32_e32 v5, 5, v8
	v_ashrrev_i16_sdwa v1, v189, sext(v1) dst_sel:DWORD dst_unused:UNUSED_PAD src0_sel:DWORD src1_sel:BYTE_0
	v_and_b32_e32 v5, 32, v5
	v_bfe_i32 v10, v1, 0, 16
	v_add_lshl_u32 v1, v5, v10, 1
	v_lshl_add_u32 v128, v4, 11, v1
	v_lshl_add_u32 v130, v3, 11, v1
	v_bfe_i32 v1, v14, 27, 1
	v_lshrrev_b32_e32 v1, 22, v1
	v_add_u32_e32 v1, v0, v1
	v_and_b32_e32 v1, 0xfffffc00, v1
	v_sub_u32_e32 v0, v0, v1
	v_lshrrev_b32_e32 v1, 4, v0
	v_bitop3_b32 v1, v1, v0, 32 bitop3:0x6c
	v_ashrrev_i32_e32 v0, 31, v0
	v_lshrrev_b32_e32 v0, 26, v0
	v_add_u32_e32 v0, v1, v0
	v_ashrrev_i32_e32 v11, 6, v0
	v_ashrrev_i32_e32 v0, 31, v14
	v_lshrrev_b32_e32 v0, 26, v0
	v_add_u32_e32 v0, v14, v0
	v_ashrrev_i32_e32 v12, 6, v0
	v_lshlrev_b32_e32 v0, 3, v12
	v_and_b32_e32 v0, -16, v0
	s_addc_u32 s33, s5, 0
	v_add_u32_e32 v0, v11, v0
	v_and_b32_e32 v2, 3, v11
	s_ashr_i32 s37, s26, 31
	v_and_or_b32 v2, v0, s4, v2
	s_lshr_b32 s4, s37, 29
	s_add_i32 s4, s26, s4
	s_ashr_i32 s12, s7, 6
	s_ashr_i32 s5, s4, 3
	s_and_b32 s4, s4, -8
	s_ashr_i32 s13, s7, 8
	s_lshl_b32 s36, s12, 10
	s_sub_i32 s4, s26, s4
	s_cmp_lt_i32 s4, 0
	s_movk_i32 s6, 0x59
	s_cselect_b32 s6, s6, 0x58
	s_mul_i32 s4, s4, s6
	s_add_i32 s4, s4, s5
	s_mul_hi_i32 s5, s4, 0x2e8ba2e9
	s_lshr_b32 s6, s5, 31
	s_ashr_i32 s5, s5, 5
	s_add_i32 s5, s5, s6
	s_lshl_b32 s14, s5, 3
	s_mulk_i32 s5, 0xb0
	s_sub_i32 s4, s4, s5
	s_bfe_u32 s5, s4, 0x3001c
	s_add_i32 s5, s4, s5
	s_sext_i32_i16 s6, s5
	s_and_b32 s5, s5, 0xfff8
	s_sub_i32 s4, s4, s5
	s_sext_i32_i16 s4, s4
	s_add_i32 s5, s14, s4
	s_ashr_i32 s4, s5, 31
	s_lshr_b32 s4, s4, 27
	s_add_i32 s14, s5, s4
	s_ashr_i32 s4, s14, 5
	s_andn2_b32 s14, s14, 31
	s_sub_i32 s24, s5, s14
	s_ashr_i32 s5, s4, 31
	s_ashr_i32 s25, s24, 31
	s_lshr_b32 s6, s6, 3
	s_lshl_b64 s[4:5], s[4:5], 11
	s_lshl_b64 s[14:15], s[24:25], 19
	v_lshrrev_b32_e32 v3, 2, v0
	v_lshlrev_b32_e32 v4, 1, v0
	s_add_u32 s16, s27, s14
	v_and_b32_e32 v3, 4, v3
	v_and_b32_e32 v4, 24, v4
	s_addc_u32 s17, s30, s15
	s_bfe_i64 s[14:15], s[6:7], 0x100000
	v_or3_b32 v2, v2, v3, v4
	v_mul_i32_i24_e32 v4, 64, v11
	s_lshl_b64 s[14:15], s[14:15], 19
	v_sub_u32_e32 v1, v1, v4
	s_add_u32 s14, s31, s14
	v_lshlrev_b32_e32 v3, 5, v12
	v_ashrrev_i16_sdwa v1, v189, sext(v1) dst_sel:DWORD dst_unused:UNUSED_PAD src0_sel:DWORD src1_sel:BYTE_0
	s_addc_u32 s15, s33, s15
	v_and_b32_e32 v3, 32, v3
	s_waitcnt vmcnt(7)
	v_bfe_i32 v13, v1, 0, 16
	s_add_u32 s42, s14, s4
	v_add_lshl_u32 v1, v3, v13, 1
	s_addc_u32 s43, s15, s5
	s_add_i32 s38, s36, 0
	v_lshl_add_u32 v144, v2, 11, v1
	s_add_i32 m0, s38, 0x10000
	v_lshl_add_u32 v132, v0, 11, v1
	global_load_lds_dwordx4 v144, s[42:43]
	s_add_i32 m0, s38, 0x12000
	s_add_u32 s14, s42, 0x40000
	global_load_lds_dwordx4 v128, s[42:43]
	s_addc_u32 s15, s43, 0
	s_add_i32 m0, s38, 0x14000
	v_mov_b32_e32 v129, v145
	global_load_lds_dwordx4 v144, s[14:15]
	s_add_i32 m0, s38, 0x16000
	s_add_u32 s54, s16, s4
	s_addc_u32 s55, s17, s5
	s_add_i32 s40, s38, 0x2000
	global_load_lds_dwordx4 v128, s[14:15]
	v_cmp_eq_u32_e32 vcc, 0, v147
	s_and_saveexec_b64 s[100:101], vcc
	s_cbranch_execz .Lgw_skip_fi
	v_readlane_b32 s56, v255, 54
	v_readlane_b32 s57, v255, 55
	v_readlane_b32 s58, v255, 50
	v_readlane_b32 s59, v255, 51
	v_readlane_b32 s60, v255, 52
	v_readlane_b32 s61, v255, 53
	s_mov_b32 s62, 0
	s_nop 1
	v_mov_b32_e32 v20, s58
	v_mov_b32_e32 v21, s60
	s_nop 1
.Lgw_poll_fi:
	global_load_dword v22, v20, s[56:57] sc1
	global_load_dword v23, v21, s[56:57] sc1
	s_waitcnt vmcnt(0)
	v_readfirstlane_b32 s63, v22
	v_readfirstlane_b32 s82, v23
	s_nop 0
	s_cmp_ge_u32 s63, s59
	s_cselect_b32 s63, 1, 0
	s_cmp_ge_u32 s82, s61
	s_cselect_b32 s82, 1, 0
	s_and_b32 s63, s63, s82
	s_cmp_lg_u32 s63, 0
	s_cbranch_scc1 .Lgw_skip_fi
	s_sleep 1
	s_add_u32 s62, s62, 1
	s_cmp_lt_u32 s62, 0x2000
	s_cbranch_scc1 .Lgw_poll_fi
.Lgw_skip_fi:
	s_or_b64 exec, exec, s[100:101]
	s_barrier
	s_mov_b32 m0, s38
	s_add_u32 s4, s54, 0x40000
	global_load_lds_dwordx4 v132, s[54:55]
	s_mov_b32 m0, s40
	s_addc_u32 s5, s55, 0
	s_add_i32 s41, s38, 0x4000
	global_load_lds_dwordx4 v130, s[54:55]
	s_mov_b32 m0, s41
	s_add_i32 s44, s38, 0x6000
	global_load_lds_dwordx4 v132, s[4:5]
	s_mov_b32 m0, s44
	v_mov_b32_e32 v133, v145
	global_load_lds_dwordx4 v130, s[4:5]
	v_mov_b32_e32 v131, v145
	s_cmp_eq_u32 s13, 1
	v_lshl_add_u64 v[6:7], s[42:43], 0, v[144:145]
	v_lshl_add_u64 v[4:5], s[42:43], 0, v[128:129]
	v_lshl_add_u64 v[0:1], s[54:55], 0, v[132:133]
	s_cselect_b64 s[4:5], -1, 0
	s_cmp_lg_u32 s13, 1
	v_lshl_add_u64 v[2:3], s[54:55], 0, v[130:131]
	s_cbranch_scc1 .LBB0_339
	s_barrier

.Lgs_nocw_b2:
	v_writelane_b32 v255, s30, 50
	v_writelane_b32 v255, s15, 51
	v_writelane_b32 v255, s30, 52
	v_writelane_b32 v255, s15, 53
	v_writelane_b32 v255, s12, 54
	v_writelane_b32 v255, s13, 55

.LBB0_443:
	v_ashrrev_i32_e32 v1, 31, v8
	v_lshrrev_b32_e32 v1, 26, v1
	v_add_u32_e32 v1, v8, v1
	v_ashrrev_i32_e32 v9, 6, v1
	v_bfe_i32 v1, v8, 27, 1
	v_lshlrev_b32_e32 v0, 4, v8
	v_lshrrev_b32_e32 v1, 22, v1
	v_add_u32_e32 v1, v0, v1
	v_and_b32_e32 v1, 0xfffffc00, v1
	v_sub_u32_e32 v1, v0, v1
	s_mul_i32 s6, s2, 0x580000
	s_mul_i32 s2, s70, 0x2800000
	v_lshrrev_b32_e32 v2, 4, v1
	s_waitcnt lgkmcnt(0)
	s_add_u32 s9, s4, s2
	v_bitop3_b32 v2, v2, v1, 32 bitop3:0x6c
	v_ashrrev_i32_e32 v1, 31, v1
	s_addc_u32 s13, s5, 0
	v_lshrrev_b32_e32 v1, 26, v1
	s_add_u32 s2, s4, 0x5800000
	v_lshlrev_b32_e32 v3, 3, v9
	v_add_u32_e32 v1, v2, v1
	s_addc_u32 s30, s5, 0
	v_and_b32_e32 v3, -16, v3
	v_ashrrev_i32_e32 v11, 6, v1
	s_add_u32 s6, s9, s6
	v_add_u32_e32 v1, v11, v3
	v_lshlrev_b32_e32 v3, 5, v9
	s_addc_u32 s9, s13, 0
	v_and_b32_e32 v10, 32, v3
	v_mul_i32_i24_e32 v3, 64, v11
	s_add_u32 s31, s6, 0xde00000
	v_sub_u32_e32 v2, v2, v3
	s_addc_u32 s33, s9, 0
	v_ashrrev_i16_sdwa v2, v189, sext(v2) dst_sel:DWORD dst_unused:UNUSED_PAD src0_sel:DWORD src1_sel:BYTE_0
	v_lshlrev_b32_e32 v3, 1, v1
	v_lshrrev_b32_e32 v4, 2, v1
	v_and_b32_e32 v5, 3, v11
	s_mov_b32 s9, 0xffffe0
	v_bfe_i32 v12, v2, 0, 16
	v_and_b32_e32 v3, 24, v3
	v_and_b32_e32 v4, 4, v4
	v_and_or_b32 v5, v1, s9, v5
	s_movk_i32 s13, 0xb00
	v_add_u32_e32 v2, v10, v12
	v_or3_b32 v3, v5, v4, v3
	v_mul_lo_u32 v1, v1, s13
	v_add_lshl_u32 v128, v2, v1, 1
	v_mul_u32_u24_e32 v1, 0xb00, v3
	v_add_u32_e32 v0, 0x2000, v0
	v_add_lshl_u32 v130, v1, v2, 1
	v_ashrrev_i32_e32 v1, 31, v0
	v_lshrrev_b32_e32 v1, 22, v1
	v_add_u32_e32 v1, v0, v1
	v_ashrrev_i32_e32 v13, 10, v1
	v_mul_i32_i24_e32 v1, 0x400, v13
	v_sub_u32_e32 v0, v0, v1
	v_lshrrev_b32_e32 v1, 4, v0
	v_bitop3_b32 v0, v1, v0, 32 bitop3:0x6c
	v_ashrrev_i32_e32 v2, 31, v0
	v_lshrrev_b32_e32 v2, 26, v2
	s_add_i32 s7, s8, s7
	v_lshlrev_b32_e32 v1, 3, v13
	v_add_u32_e32 v2, v0, v2
	s_ashr_i32 s8, s7, 31
	v_and_b32_e32 v1, -16, v1
	v_ashrrev_i32_e32 v15, 6, v2
	s_lshr_b32 s8, s8, 27
	v_add_u32_e32 v1, v15, v1
	v_and_b32_e32 v4, 3, v15
	s_add_i32 s8, s7, s8
	v_and_or_b32 v4, v1, s9, v4
	s_ashr_i32 s9, s8, 5
	s_and_b32 s8, s8, 0xffe0
	s_sub_i32 s8, s7, s8
	s_bfe_i32 s7, s8, 0x80000
	s_bfe_u32 s7, s7, 0x3000c
	s_add_i32 s14, s8, s7
	s_bfe_i32 s7, s14, 0x80000
	s_and_b32 s14, s14, 0xf8
	s_sub_i32 s8, s8, s14
	s_lshl_b32 s9, s9, 3
	s_sext_i32_i8 s8, s8
	s_add_i32 s8, s9, s8
	s_ashr_i32 s9, s8, 31
	s_lshr_b32 s9, s9, 27
	s_add_i32 s9, s8, s9
	s_ashr_i32 s16, s9, 5
	s_andn2_b32 s9, s9, 31
	v_lshlrev_b32_e32 v3, 5, v13
	v_and_b32_e32 v2, 0xc0, v2
	s_sext_i32_i16 s15, s7
	s_sub_i32 s54, s8, s9
	v_and_b32_e32 v14, 32, v3
	v_sub_u32_e32 v0, v0, v2
	v_lshlrev_b32_e32 v2, 1, v1
	v_lshrrev_b32_e32 v3, 2, v1
	v_mul_lo_u32 v1, v1, s13
	s_ashr_i32 s13, s12, 6
	s_lshr_b32 s7, s15, 3
	s_mul_i32 s8, s54, 0x160000
	s_ashr_i32 s15, s15, 3
	s_ashr_i32 s6, s12, 8
	s_lshl_b32 s36, s13, 10
	s_ashr_i32 s9, s8, 31
	s_mul_hi_i32 s18, s15, 0x160000
	s_mul_i32 s15, s15, 0x160000
	s_add_u32 s15, s31, s15
	s_mul_i32 s17, s16, 0xb00
	s_addc_u32 s18, s33, s18
	s_mul_hi_i32 s14, s16, 0xb00
	s_add_u32 s20, s15, s17
	s_addc_u32 s21, s18, s14
	s_add_i32 s37, s36, 0
	v_ashrrev_i16_sdwa v0, v189, sext(v0) dst_sel:DWORD dst_unused:UNUSED_PAD src0_sel:DWORD src1_sel:BYTE_0
	s_add_i32 m0, s37, 0x10000
	v_bfe_i32 v16, v0, 0, 16
	v_and_b32_e32 v2, 24, v2
	v_and_b32_e32 v3, 4, v3
	global_load_lds_dwordx4 v130, s[20:21]
	s_add_i32 m0, s37, 0x12000
	v_add_u32_e32 v0, v14, v16
	v_or3_b32 v2, v4, v3, v2
	s_add_u32 s15, s2, s8
	v_add_lshl_u32 v132, v0, v1, 1
	v_mul_u32_u24_e32 v1, 0xb00, v2
	s_addc_u32 s19, s30, s9
	v_add_lshl_u32 v134, v1, v0, 1
	s_add_u32 s8, s20, 0xb0000
	global_load_lds_dwordx4 v134, s[20:21]
	s_addc_u32 s9, s21, 0
	s_add_i32 m0, s37, 0x14000
	v_mov_b32_e32 v131, v145
	global_load_lds_dwordx4 v130, s[8:9]
	s_add_i32 m0, s37, 0x16000
	s_add_u32 s18, s15, s17
	s_addc_u32 s19, s19, s14
	s_add_i32 s40, s37, 0x2000
	global_load_lds_dwordx4 v134, s[8:9]
	v_cmp_eq_u32_e32 vcc, 0, v147
	s_and_saveexec_b64 s[100:101], vcc
	s_cbranch_execz .Lgw_skip_fo
	v_readlane_b32 s56, v255, 54
	v_readlane_b32 s57, v255, 55
	v_readlane_b32 s58, v255, 50
	v_readlane_b32 s59, v255, 51
	v_readlane_b32 s60, v255, 52
	v_readlane_b32 s61, v255, 53
	s_mov_b32 s62, 0
	s_nop 1
	v_mov_b32_e32 v20, s58
	v_mov_b32_e32 v21, s60
	s_nop 1

.Lgw_skip_fo:
	s_or_b64 exec, exec, s[100:101]
	s_barrier
	s_mov_b32 m0, s37
	s_add_u32 s8, s18, 0xb0000
	global_load_lds_dwordx4 v128, s[18:19]
	s_mov_b32 m0, s40
	s_addc_u32 s9, s19, 0
	s_add_i32 s41, s37, 0x4000
	global_load_lds_dwordx4 v132, s[18:19]
	s_mov_b32 m0, s41
	s_add_i32 s42, s37, 0x6000
	global_load_lds_dwordx4 v128, s[8:9]
	s_mov_b32 m0, s42
	v_mov_b32_e32 v135, v145
	global_load_lds_dwordx4 v132, s[8:9]
	v_mov_b32_e32 v129, v145
	v_mov_b32_e32 v133, v145
	s_cmp_eq_u32 s6, 1
	v_lshl_add_u64 v[6:7], s[20:21], 0, v[130:131]
	v_lshl_add_u64 v[4:5], s[20:21], 0, v[134:135]
	v_lshl_add_u64 v[0:1], s[18:19], 0, v[128:129]
	s_cselect_b64 s[8:9], -1, 0
	s_cmp_lg_u32 s6, 1
	v_lshl_add_u64 v[2:3], s[18:19], 0, v[132:133]
	s_cbranch_scc1 .LBB0_445
	s_barrier

.Lxb_noinv_4:
	v_cmp_eq_u32_e32 vcc, 0, v0
	s_and_saveexec_b64 s[4:5], vcc
	s_cbranch_execz .LBB0_575
	s_load_dwordx2 s[12:13], s[16:17], 0x98
	v_readlane_b32 s14, v255, 0
	v_readlane_b32 s15, v255, 47
	s_nop 0
	s_lshr_b32 s24, s14, 3
	s_and_b32 s24, s24, 7
	s_and_b32 s27, s14, 6
	s_lshl_b32 s27, s27, 2
	s_or_b32 s27, s27, s24
	s_and_b32 s30, s14, 3
	s_lshl_b32 s30, s30, 3
	s_or_b32 s30, s30, s24
	s_lshl_b32 s27, s27, 7
	s_add_u32 s27, s27, 0xb000
	s_add_u32 s15, s15, 8
	v_writelane_b32 v255, s15, 47
	v_mov_b32_e32 v0, s27
	s_waitcnt lgkmcnt(0)
	global_atomic_add v0, v189, s[12:13]
	v_writelane_b32 v255, s27, 50
	v_writelane_b32 v255, s15, 51
	v_writelane_b32 v255, s27, 52
	v_writelane_b32 v255, s15, 53
	v_writelane_b32 v255, s12, 54
	v_writelane_b32 v255, s13, 55

.LBB0_581:
	s_andn2_b64 vcc, exec, s[10:11]
	s_cbranch_vccnz .LBB0_921
	v_ashrrev_i32_e32 v1, 31, v10
	v_lshrrev_b32_e32 v1, 26, v1
	v_add_u32_e32 v1, v10, v1
	v_ashrrev_i32_e32 v8, 6, v1
	v_bfe_i32 v1, v10, 27, 1
	v_lshlrev_b32_e32 v0, 4, v10
	v_lshrrev_b32_e32 v1, 22, v1
	v_add_u32_e32 v1, v0, v1
	v_and_b32_e32 v1, 0xfffffc00, v1
	v_sub_u32_e32 v1, v0, v1
	v_lshrrev_b32_e32 v2, 4, v1
	v_bitop3_b32 v2, v2, v1, 32 bitop3:0x6c
	v_ashrrev_i32_e32 v1, 31, v1
	v_lshrrev_b32_e32 v1, 26, v1
	v_add_u32_e32 v1, v2, v1
	s_mul_i32 s7, s70, 0x2800000
	v_ashrrev_i32_e32 v9, 6, v1
	s_waitcnt lgkmcnt(0)
	s_add_u32 s7, s14, s7
	v_lshlrev_b32_e32 v3, 3, v8
	v_mul_i32_i24_e32 v4, 64, v9
	s_addc_u32 s9, s15, 0
	v_and_b32_e32 v3, -16, v3
	v_sub_u32_e32 v2, v2, v4
	s_add_u32 s51, s14, 0x1000000
	v_add_u32_e32 v1, v9, v3
	v_lshlrev_b32_e32 v3, 5, v8
	v_ashrrev_i16_sdwa v2, v189, sext(v2) dst_sel:DWORD dst_unused:UNUSED_PAD src0_sel:DWORD src1_sel:BYTE_0
	s_addc_u32 s71, s15, 0
	v_and_b32_e32 v3, 32, v3
	v_bfe_i32 v11, v2, 0, 16
	s_add_u32 s78, s7, 0xe900000
	v_and_b32_e32 v5, 3, v9
	s_mov_b32 s7, 0x1fffe0
	v_add_lshl_u32 v3, v3, v11, 1
	v_add_u32_e32 v0, 0x2000, v0
	v_lshlrev_b32_e32 v2, 1, v1
	v_lshrrev_b32_e32 v4, 2, v1
	v_and_or_b32 v5, v1, s7, v5
	v_lshl_add_u32 v132, v1, 11, v3
	v_ashrrev_i32_e32 v1, 31, v0
	v_lshrrev_b32_e32 v1, 22, v1
	v_add_u32_e32 v1, v0, v1
	v_ashrrev_i32_e32 v12, 10, v1
	v_mul_i32_i24_e32 v1, 0x400, v12
	v_sub_u32_e32 v0, v0, v1
	v_and_b32_e32 v2, 24, v2
	v_and_b32_e32 v4, 4, v4
	v_lshrrev_b32_e32 v1, 4, v0
	v_or3_b32 v2, v5, v4, v2
	v_bitop3_b32 v0, v1, v0, 32 bitop3:0x6c
	v_lshl_add_u32 v134, v2, 11, v3
	v_ashrrev_i32_e32 v2, 31, v0
	v_lshrrev_b32_e32 v2, 26, v2
	v_lshlrev_b32_e32 v1, 3, v12
	v_add_u32_e32 v2, v0, v2
	v_and_b32_e32 v1, -16, v1
	v_ashrrev_i32_e32 v13, 6, v2
	v_add_u32_e32 v1, v13, v1
	v_and_b32_e32 v4, 3, v13
	s_addc_u32 s79, s9, 0
	v_and_or_b32 v4, v1, s7, v4
	s_ashr_i32 s11, s2, 6
	s_ashr_i32 s7, s6, 31
	s_ashr_i32 s10, s2, 8
	s_lshl_b32 s86, s11, 10
	s_lshl_b64 s[18:19], s[6:7], 19
	s_add_u32 s7, s51, s18
	s_addc_u32 s20, s71, s19
	s_ashr_i32 s9, s8, 31
	s_lshl_b64 s[18:19], s[8:9], 19
	v_and_b32_e32 v2, 0xc0, v2
	s_add_u32 s9, s78, s18
	v_sub_u32_e32 v0, v0, v2
	s_addc_u32 s18, s79, s19
	v_ashrrev_i16_sdwa v0, v189, sext(v0) dst_sel:DWORD dst_unused:UNUSED_PAD src0_sel:DWORD src1_sel:BYTE_0
	s_add_u32 s42, s9, s4
	v_lshlrev_b32_e32 v3, 5, v12
	v_bfe_i32 v14, v0, 0, 16
	v_lshlrev_b32_e32 v0, 1, v1
	v_lshrrev_b32_e32 v2, 2, v1
	s_addc_u32 s43, s18, s5
	s_add_i32 s87, s86, 0
	v_and_b32_e32 v3, 32, v3
	v_and_b32_e32 v0, 24, v0
	v_and_b32_e32 v2, 4, v2
	s_add_i32 m0, s87, 0x10000
	v_or3_b32 v0, v4, v2, v0
	v_add_lshl_u32 v2, v3, v14, 1
	global_load_lds_dwordx4 v134, s[42:43]
	s_add_i32 m0, s87, 0x12000
	v_lshl_add_u32 v138, v0, 11, v2
	s_add_u32 s18, s42, 0x40000
	global_load_lds_dwordx4 v138, s[42:43]
	s_addc_u32 s19, s43, 0
	s_add_i32 m0, s87, 0x14000
	v_lshl_add_u32 v136, v1, 11, v2
	global_load_lds_dwordx4 v134, s[18:19]
	s_add_i32 m0, s87, 0x16000
	s_add_u32 s4, s7, s4
	s_addc_u32 s5, s20, s5
	s_add_i32 s76, s87, 0x2000
	global_load_lds_dwordx4 v138, s[18:19]
	v_cmp_eq_u32_e32 vcc, 0, v147
	s_and_saveexec_b64 s[100:101], vcc
	s_cbranch_execz .Lgw_skip_mi
	v_readlane_b32 s56, v255, 54
	v_readlane_b32 s57, v255, 55
	v_readlane_b32 s58, v255, 50
	v_readlane_b32 s59, v255, 51
	v_readlane_b32 s60, v255, 52
	v_readlane_b32 s61, v255, 53
	s_mov_b32 s62, 0
	s_nop 1
	v_mov_b32_e32 v20, s58
	v_mov_b32_e32 v21, s60
	s_nop 1

.Lgw_skip_mi:
	s_or_b64 exec, exec, s[100:101]
	s_barrier
	s_mov_b32 m0, s87
	s_add_u32 s18, s4, 0x40000
	global_load_lds_dwordx4 v132, s[4:5]
	s_mov_b32 m0, s76
	s_addc_u32 s19, s5, 0
	s_add_i32 s77, s87, 0x4000
	global_load_lds_dwordx4 v136, s[4:5]
	s_mov_b32 m0, s77
	s_add_i32 s74, s87, 0x6000
	global_load_lds_dwordx4 v132, s[18:19]
	s_mov_b32 m0, s74
	v_mov_b32_e32 v135, v145
	global_load_lds_dwordx4 v136, s[18:19]
	v_mov_b32_e32 v139, v145
	v_mov_b32_e32 v133, v145
	v_mov_b32_e32 v137, v145
	s_cmp_eq_u32 s10, 1
	v_lshl_add_u64 v[6:7], s[42:43], 0, v[134:135]
	v_lshl_add_u64 v[4:5], s[42:43], 0, v[138:139]
	v_lshl_add_u64 v[0:1], s[4:5], 0, v[132:133]
	s_cselect_b64 s[18:19], -1, 0
	s_cmp_lg_u32 s10, 1
	v_lshl_add_u64 v[2:3], s[4:5], 0, v[136:137]
	s_cbranch_scc1 .LBB0_584
	s_barrier

.Lxb_noinv_8:
	v_cmp_eq_u32_e32 vcc, 0, v0
	s_and_saveexec_b64 s[4:5], vcc
	s_cbranch_execz .LBB0_334
	s_load_dwordx2 s[12:13], s[8:9], 0x98
	v_readlane_b32 s14, v255, 0
	v_readlane_b32 s15, v255, 47
	s_nop 0
	s_lshr_b32 s24, s14, 3
	s_and_b32 s24, s24, 7
	s_and_b32 s27, s14, 6
	s_lshl_b32 s27, s27, 2
	s_or_b32 s27, s27, s24
	s_and_b32 s30, s14, 3
	s_lshl_b32 s30, s30, 3
	s_or_b32 s30, s30, s24
	s_lshl_b32 s27, s27, 7
	s_add_u32 s27, s27, 0xb000
	s_add_u32 s15, s15, 8
	v_writelane_b32 v255, s15, 47
	v_mov_b32_e32 v0, s27
	s_waitcnt lgkmcnt(0)
	global_atomic_add v0, v189, s[12:13]
	v_writelane_b32 v255, s27, 50
	v_writelane_b32 v255, s15, 51
	v_writelane_b32 v255, s27, 52
	v_writelane_b32 v255, s15, 53
	v_writelane_b32 v255, s12, 54
	v_writelane_b32 v255, s13, 55
	s_branch .LBB0_334
